# deferred-tile completion counter sharded 8 ways (publisher and pollers use the word of their own bid&7 group)
# baseline (speedup 1.0000x reference)
; #define LAS __attribute__((address_space(3)))
; __device__ __forceinline__ int opaque_bid() { int t = blockIdx.x; asm volatile("" : "+s"(t)); return t; }
; __global__ void __launch_bounds__(512, 2) hymba_fwd(Params p0) {
;     ...
;         case 5: if (PH_MASK & 32) { pg8::Gemm g{(const bf16_t*)(p.ws + WS_A2), (const bf16_t*)(p.ws + WS_WUP), MP, N3, 2048}; pg8::StaticOrder S; S.init(MP, N3, gridDim.x, opaque_bid());
;                   Epi3 E{(bf16_t*)(p.ws + WS_UP), (const float*)(p.ws + WS_SS2)}; pg8::gemm_phase((LAS unsigned char*)smem, g, S, E);
;                   convert_in_tail(p, smem, (MP / 256) * (N3 / 256), T_IN + T_OUT + T_UP, T_ALL); } break;
.Lp5_tail_tile:
	s_sub_i32 s9, s14, 0x580
	s_mul_i32 s8, s9, 0xcccd
	s_lshr_b32 s8, s8, 18
	s_mul_i32 s13, s8, 5
	s_sub_i32 s13, s9, s13
	s_add_i32 s12, s13, 32
	s_and_b32 s16, s26, 7
	s_lshl_b32 s16, s16, 6
	s_add_u32 s16, s16, 0x22b32500
	s_add_u32 s16, s82, s16
	s_addc_u32 s17, s83, 0
	s_mov_b32 s9, 0
.Lp5_wait_deferred:
	global_load_dword v4, v149, s[16:17] sc1
	s_waitcnt vmcnt(0)
	v_readfirstlane_b32 s13, v4
	s_cmpk_ge_u32 s13, 5
	s_cbranch_scc1 .Lp5_deferred_ready
	s_add_i32 s9, s9, 1
	s_cmp_ge_u32 s9, 0x40000
	s_cbranch_scc1 .Lp5_deferred_ready
	s_sleep 4
	s_branch .Lp5_wait_deferred

; #define LAS __attribute__((address_space(3)))
; __device__ __forceinline__ int opaque_bid() { int t = blockIdx.x; asm volatile("" : "+s"(t)); return t; }
; __global__ void __launch_bounds__(512, 2) hymba_fwd(Params p0) {
;     ...
;         case 4: if (PH_MASK & 16) { pg8::Gemm g{(const bf16_t*)(p.ws + WS_MIX), (const bf16_t*)(p.ws + WS_WOUT), MP, 2048, 4096}; pg8::StaticOrder S; S.init(MP, 2048, gridDim.x, opaque_bid());
;                   Epi2 E{p}; pg8::gemm_phase((LAS unsigned char*)smem, g, S, E);
;                   convert_in_tail(p, smem, (MP / 256) * (2048 / 256), T_IN + T_OUT, T_IN + T_OUT + T_UP); } break;
.LBB0_328:
	s_barrier
	v_readlane_b32 s0, v255, 61
	s_nop 0
	s_cmp_lg_u32 s0, 1
	s_cbranch_scc1 .LBB0_415
	s_mov_b32 s0, 2
	s_nop 0
	v_writelane_b32 v255, s0, 61
	v_cmp_eq_u32_e32 vcc, 0, v151
	s_and_saveexec_b64 s[4:5], vcc
	s_cbranch_execz .Lp4_deferred_published
	buffer_wbl2 sc1
	s_waitcnt vmcnt(0)
	v_readlane_b32 s0, v254, 0
	s_nop 0
	s_and_b32 s0, s0, 7
	s_lshl_b32 s0, s0, 6
	s_add_u32 s0, s0, 0x22b32500
	s_add_u32 s0, s82, s0
	s_addc_u32 s1, s83, 0
	v_mov_b32_e32 v4, 1
	global_atomic_add v149, v4, s[0:1]
	s_waitcnt vmcnt(0)
